# plus: phi-bias reduction loop rewritten with 16 loads in flight per iteration (was one dependent round trip per element)
# speedup vs baseline: 1.0109x; 1.0109x over previous
.LBB0_726:
	s_mov_b64 s[0:1], s[88:89]
	s_mov_b32 s3, s67
	s_mov_b32 s4, s68
	s_sub_i32 s5, s4, 32
	s_cmp_gt_i32 s3, 63
	s_cselect_b32 s4, s5, s4
	s_mov_b32 s2, s76
	v_mov_b32_e32 v4, v213
	s_cmp_gt_u32 s4, 15
	s_cbranch_scc1 .LBB0_746
	s_cmp_lt_u32 s4, 8
	s_cselect_b32 s3, 48, 56
	s_cselect_b32 s5, 64, 0x50
	s_add_u32 s6, s0, s3
	s_addc_u32 s7, s1, 0
	s_ashr_i32 s3, s2, 31
	s_lshl_b64 s[8:9], s[2:3], 13
	s_add_u32 s10, s0, s5
	s_addc_u32 s11, s1, 0
	v_lshlrev_b32_e32 v0, 2, v4
	s_load_dwordx2 s[6:7], s[6:7], 0x0
	s_nop 0
	s_load_dwordx2 s[10:11], s[10:11], 0x0
	v_and_b32_e32 v2, 0xffffff80, v0
	s_lshl_b64 s[12:13], s[2:3], 21
	s_lshl_b32 s3, s4, 5
	v_ashrrev_i32_e32 v3, 31, v2
	s_and_b32 s24, s3, 0xe0
	v_or_b32_e32 v5, 0x7f, v0
	v_lshlrev_b64 v[0:1], 10, v[2:3]
	v_and_or_b32 v7, v4, 31, s24
	v_lshl_add_u64 v[0:1], s[12:13], 0, v[0:1]
	v_lshl_or_b32 v0, v7, 2, v0
	s_waitcnt lgkmcnt(0)
	v_lshl_add_u64 v[0:1], s[10:11], 0, v[0:1]
	s_mov_b64 s[4:5], 0x1000
	v_lshl_add_u64 v[0:1], v[0:1], 0, s[4:5]
	s_add_u32 s4, s6, s8
	s_addc_u32 s5, s7, s9
	v_or_b32_e32 v6, 2, v2
	v_lshl_add_u64 v[2:3], v[2:3], 2, s[4:5]
	v_lshl_add_u64 v[2:3], v[2:3], 0, 28
	v_mov_b32_e32 v7, 0
	s_mov_b64 s[4:5], 0
	s_mov_b32 s6, 16
.Lbias_loop:
	global_load_dword v8, v[2:3], off offset:-28
	global_load_dword v9, v[0:1], off offset:-4096
	global_load_dword v10, v[2:3], off offset:-24
	global_load_dword v11, v[0:1], off offset:-3072
	global_load_dword v12, v[2:3], off offset:-20
	global_load_dword v13, v[0:1], off offset:-2048
	global_load_dword v14, v[2:3], off offset:-16
	global_load_dword v15, v[0:1], off offset:-1024
	global_load_dword v16, v[2:3], off offset:-12
	global_load_dword v17, v[0:1], off
	global_load_dword v18, v[2:3], off offset:-8
	global_load_dword v19, v[0:1], off offset:1024
	global_load_dword v20, v[2:3], off offset:-4
	global_load_dword v21, v[0:1], off offset:2048
	global_load_dword v22, v[2:3], off
	global_load_dword v23, v[0:1], off offset:3072
	s_mov_b64 s[20:21], 0x2000
	v_lshl_add_u64 v[0:1], v[0:1], 0, s[20:21]
	v_lshl_add_u64 v[2:3], v[2:3], 0, 32
	s_waitcnt vmcnt(0)
	v_fmac_f32_e32 v7, v8, v9
	v_fmac_f32_e32 v7, v10, v11
	v_fmac_f32_e32 v7, v12, v13
	v_fmac_f32_e32 v7, v14, v15
	v_fmac_f32_e32 v7, v16, v17
	v_fmac_f32_e32 v7, v18, v19
	v_fmac_f32_e32 v7, v20, v21
	v_fmac_f32_e32 v7, v22, v23
	s_sub_i32 s6, s6, 1
	s_cmp_lg_u32 s6, 0
	s_cbranch_scc1 .Lbias_loop
